# v66 + pre_phase: skip path retires its own unconsumed loads, store-only waits dropped; LoRA epilogue store-only waits dropped
# baseline (speedup 1.0000x reference)
.Lpre_skip2:
	s_waitcnt vmcnt(2)

.LBB0_889:
	v_add_u32_e32 v0, s24, v45
	s_nop 0
	v_min_i32_e32 v4, 0xaff, v0
	v_cmp_lt_i32_e32 vcc, s68, v0
	s_and_saveexec_b64 s[24:25], vcc
	s_xor_b64 s[24:25], exec, s[24:25]
	s_cbranch_execz .LBB0_895
	s_movk_i32 s26, 0x9ff
	v_cmp_lt_u32_e64 s[44:45], s26, v0
	v_lshlrev_b32_e32 v5, 3, v4
	s_and_saveexec_b64 s[26:27], s[44:45]
	s_xor_b64 s[26:27], exec, s[26:27]
	v_add_u32_e32 v2, 0xfffff600, v4
	v_lshrrev_b32_e32 v3, 4, v2
	v_and_b32_e32 v2, 0x78, v5
	v_or_b32_e32 v2, 0x500, v2
	s_andn2_saveexec_b64 s[26:27], s[26:27]
	v_add_u32_e32 v2, 0xfffff700, v4
	v_bfe_u32 v3, v4, 3, 4
	v_lshrrev_b32_e32 v2, 1, v2
	v_and_b32_e32 v4, 56, v5
	v_and_or_b32 v2, v2, s37, v4
	v_add_u32_e32 v2, 0x480, v2
	s_or_b64 exec, exec, s[26:27]

.LBB0_897:
	s_or_b64 exec, exec, s[24:25]
	v_add_u32_e32 v4, s13, v3
	v_cmp_lt_i32_e64 s[44:45], s91, v4
	s_and_saveexec_b64 s[24:25], s[44:45]
	s_xor_b64 s[24:25], exec, s[24:25]
	s_cbranch_execz .LBB0_899
	v_add_u32_e32 v3, 0xffffff00, v4
	v_lshlrev_b32_e32 v5, 6, v4
	s_nop 0
	v_lshrrev_b32_e32 v6, 6, v3
	v_and_or_b32 v5, v5, s96, v6
	v_cndmask_b32_e64 v3, v5, v3, s[40:41]
	v_add_u32_e32 v3, s34, v3
.LBB0_899:
	s_andn2_saveexec_b64 s[24:25], s[24:25]
	v_add_u32_e32 v3, s35, v4
	s_or_b64 exec, exec, s[24:25]
	s_nop 0
	v_mov_b64_e32 v[6:7], s[16:17]
	v_mad_i64_i32 v[6:7], s[24:25], v3, s69, v[6:7]
	v_ashrrev_i32_e32 v3, 31, v2
	v_lshl_add_u64 v[6:7], v[2:3], 1, v[6:7]
	global_load_dwordx4 v[26:29], v[6:7], off offset:1536
	v_cmp_lt_i32_e64 s[44:45], s30, v4
	s_nop 1
	v_subbrev_co_u32_e64 v5, s[44:45], 0, v4, s[44:45]
	v_cmp_lt_i32_e64 s[44:45], s91, v5
	s_and_saveexec_b64 s[24:25], s[44:45]
	s_xor_b64 s[24:25], exec, s[24:25]
	v_add_u32_e32 v6, 0xffffff00, v5
	v_lshlrev_b32_e32 v5, 6, v5
	v_lshrrev_b32_e32 v7, 6, v6
	v_and_or_b32 v5, v5, s96, v7
	v_cndmask_b32_e64 v5, v5, v6, s[40:41]
	v_add_u32_e32 v6, s34, v5
	s_andn2_saveexec_b64 s[24:25], s[24:25]
	v_add_u32_e32 v6, s35, v5
	s_or_b64 exec, exec, s[24:25]
	v_mov_b64_e32 v[8:9], s[16:17]
	v_mad_i64_i32 v[6:7], s[24:25], v6, s69, v[8:9]
	v_lshl_add_u64 v[6:7], v[2:3], 1, v[6:7]
	global_load_dwordx4 v[30:33], v[6:7], off offset:1536
	v_add_u32_e32 v5, 1, v4
	v_cmp_gt_i32_e64 s[44:45], s31, v5
	s_nop 1
	v_cndmask_b32_e64 v5, v4, v5, s[44:45]
	v_cmp_lt_i32_e64 s[44:45], s91, v5
	s_and_saveexec_b64 s[24:25], s[44:45]
	s_xor_b64 s[24:25], exec, s[24:25]
	v_add_u32_e32 v4, 0xffffff00, v5
	v_lshlrev_b32_e32 v5, 6, v5
	v_lshrrev_b32_e32 v6, 6, v4
	v_and_or_b32 v5, v5, s96, v6
	v_cndmask_b32_e64 v4, v5, v4, s[40:41]
	v_add_u32_e32 v4, s34, v4
	s_andn2_saveexec_b64 s[24:25], s[24:25]
	v_add_u32_e32 v4, s35, v5
	s_or_b64 exec, exec, s[24:25]
	v_mov_b64_e32 v[6:7], s[16:17]
	v_mad_i64_i32 v[4:5], s[24:25], v4, s69, v[6:7]
	v_lshl_add_u64 v[2:3], v[2:3], 1, v[4:5]
	global_load_dwordx4 v[34:37], v[2:3], off offset:1536
	v_add_u32_e32 v51, 0x200, v0
	v_min_i32_e32 v4, 0xaff, v51
	v_cmp_lt_i32_e64 s[46:47], s68, v51
	s_and_saveexec_b64 s[24:25], s[46:47]
	s_xor_b64 s[24:25], exec, s[24:25]
	s_cbranch_execz .LBB0_915
	s_movk_i32 s26, 0x9ff
	v_cmp_lt_u32_e64 s[44:45], s26, v51
	v_lshlrev_b32_e32 v5, 3, v4
	s_and_saveexec_b64 s[26:27], s[44:45]
	s_xor_b64 s[26:27], exec, s[26:27]
	v_add_u32_e32 v2, 0xfffff600, v4
	v_lshrrev_b32_e32 v3, 4, v2
	v_and_b32_e32 v2, 0x78, v5
	v_or_b32_e32 v2, 0x500, v2
	s_andn2_saveexec_b64 s[26:27], s[26:27]
	v_add_u32_e32 v2, 0xfffff700, v4
	v_bfe_u32 v3, v4, 3, 4
	v_lshrrev_b32_e32 v2, 1, v2
	v_and_b32_e32 v4, 56, v5
	v_and_or_b32 v2, v2, s37, v4
	v_add_u32_e32 v2, 0x480, v2
	s_or_b64 exec, exec, s[26:27]

.LBB0_917:
	s_or_b64 exec, exec, s[24:25]
	v_add_u32_e32 v4, s13, v3
	v_cmp_lt_i32_e64 s[44:45], s91, v4
	s_and_saveexec_b64 s[24:25], s[44:45]
	s_xor_b64 s[24:25], exec, s[24:25]
	v_add_u32_e32 v3, 0xffffff00, v4
	v_lshlrev_b32_e32 v5, 6, v4
	v_lshrrev_b32_e32 v6, 6, v3
	v_and_or_b32 v5, v5, s96, v6
	v_cndmask_b32_e64 v3, v5, v3, s[40:41]
	v_add_u32_e32 v3, s34, v3
	s_andn2_saveexec_b64 s[24:25], s[24:25]
	v_add_u32_e32 v3, s35, v4
	s_or_b64 exec, exec, s[24:25]
	v_mov_b64_e32 v[6:7], s[16:17]
	v_mad_i64_i32 v[6:7], s[24:25], v3, s69, v[6:7]
	v_ashrrev_i32_e32 v3, 31, v2
	v_lshl_add_u64 v[6:7], v[2:3], 1, v[6:7]
	global_load_dwordx4 v[14:17], v[6:7], off offset:1536
	v_cmp_lt_i32_e64 s[44:45], s30, v4
	s_nop 1
	v_subbrev_co_u32_e64 v5, s[44:45], 0, v4, s[44:45]
	v_cmp_lt_i32_e64 s[44:45], s91, v5
	s_and_saveexec_b64 s[24:25], s[44:45]
	s_xor_b64 s[24:25], exec, s[24:25]
	v_add_u32_e32 v6, 0xffffff00, v5
	v_lshlrev_b32_e32 v5, 6, v5
	v_lshrrev_b32_e32 v7, 6, v6
	v_and_or_b32 v5, v5, s96, v7
	v_cndmask_b32_e64 v5, v5, v6, s[40:41]
	v_add_u32_e32 v6, s34, v5
	s_andn2_saveexec_b64 s[24:25], s[24:25]
	v_add_u32_e32 v6, s35, v5
	s_or_b64 exec, exec, s[24:25]
	v_mov_b64_e32 v[8:9], s[16:17]
	v_mad_i64_i32 v[6:7], s[24:25], v6, s69, v[8:9]
	v_lshl_add_u64 v[6:7], v[2:3], 1, v[6:7]
	global_load_dwordx4 v[18:21], v[6:7], off offset:1536
	v_add_u32_e32 v5, 1, v4
	v_cmp_gt_i32_e64 s[44:45], s31, v5
	s_nop 1
	v_cndmask_b32_e64 v5, v4, v5, s[44:45]
	v_cmp_lt_i32_e64 s[44:45], s91, v5
	s_and_saveexec_b64 s[24:25], s[44:45]
	s_xor_b64 s[24:25], exec, s[24:25]
	v_add_u32_e32 v4, 0xffffff00, v5
	v_lshlrev_b32_e32 v5, 6, v5
	v_lshrrev_b32_e32 v6, 6, v4
	v_and_or_b32 v5, v5, s96, v6
	v_cndmask_b32_e64 v4, v5, v4, s[40:41]
	v_add_u32_e32 v4, s34, v4
	s_andn2_saveexec_b64 s[24:25], s[24:25]
	v_add_u32_e32 v4, s35, v5
	s_or_b64 exec, exec, s[24:25]
	v_mov_b64_e32 v[6:7], s[16:17]
	v_mad_i64_i32 v[4:5], s[24:25], v4, s69, v[6:7]
	v_lshl_add_u64 v[2:3], v[2:3], 1, v[4:5]
	global_load_dwordx4 v[22:25], v[2:3], off offset:1536
	v_add_u32_e32 v50, 0x400, v0
	v_min_i32_e32 v3, 0xaff, v50
	v_cmp_lt_i32_e64 s[44:45], s68, v50
	s_and_saveexec_b64 s[24:25], s[44:45]
	s_xor_b64 s[24:25], exec, s[24:25]
	s_cbranch_execz .LBB0_935
	s_movk_i32 s26, 0x9ff
	v_cmp_lt_u32_e64 s[48:49], s26, v50
	v_lshlrev_b32_e32 v4, 3, v3
	s_and_saveexec_b64 s[26:27], s[48:49]
	s_xor_b64 s[26:27], exec, s[26:27]
	s_cbranch_execz .LBB0_932
	v_add_u32_e32 v2, 0xfffff600, v3
	v_and_b32_e32 v3, 0x78, v4
	v_lshrrev_b32_e32 v2, 4, v2
	s_nop 0
	v_or_b32_e32 v10, 0x500, v3
.LBB0_932:
	s_andn2_saveexec_b64 s[26:27], s[26:27]
	s_cbranch_execz .LBB0_934
	v_add_u32_e32 v5, 0xfffff700, v3
	v_bfe_u32 v2, v3, 3, 4
	v_lshrrev_b32_e32 v3, 1, v5
	v_and_b32_e32 v4, 56, v4
	v_and_or_b32 v3, v3, s37, v4
	s_nop 0
	v_add_u32_e32 v10, 0x480, v3

.LBB0_935:
	s_andn2_saveexec_b64 s[24:25], s[24:25]
	s_cbranch_execz .LBB0_937
	v_mul_hi_i32 v2, v3, s11
	v_lshrrev_b32_e32 v4, 31, v2
	v_ashrrev_i32_e32 v2, 7, v2
	v_add_u32_e32 v4, v2, v4
	v_mul_i32_i24_e32 v2, 0xfffffd00, v4
	v_add_u32_e32 v3, v2, v3
	v_mul_hi_i32 v2, v3, s11
	v_lshrrev_b32_e32 v5, 31, v2
	v_ashrrev_i32_e32 v2, 3, v2
	v_add_u32_e32 v2, v2, v5
	v_mul_lo_u32 v5, v2, 48
	v_mul_i32_i24_e32 v4, 0x180, v4
	v_sub_u32_e32 v3, v3, v5
	s_nop 0
	v_lshl_add_u32 v10, v3, 3, v4
.LBB0_937:
	s_or_b64 exec, exec, s[24:25]
	s_nop 0
	v_add_u32_e32 v12, s13, v2
	v_cmp_lt_i32_e64 s[48:49], s91, v12
	s_and_saveexec_b64 s[24:25], s[48:49]
	s_xor_b64 s[24:25], exec, s[24:25]
	v_add_u32_e32 v2, 0xffffff00, v12
	v_lshlrev_b32_e32 v3, 6, v12
	v_lshrrev_b32_e32 v4, 6, v2
	v_and_or_b32 v3, v3, s96, v4
	v_cndmask_b32_e64 v2, v3, v2, s[40:41]
	v_add_u32_e32 v2, s34, v2
	s_andn2_saveexec_b64 s[24:25], s[24:25]
	v_add_u32_e32 v2, s35, v12
	s_or_b64 exec, exec, s[24:25]
	v_mov_b64_e32 v[4:5], s[16:17]
	v_mad_i64_i32 v[2:3], s[24:25], v2, s69, v[4:5]
	v_ashrrev_i32_e32 v11, 31, v10
	v_lshl_add_u64 v[2:3], v[10:11], 1, v[2:3]
	global_load_dwordx4 v[2:5], v[2:3], off offset:1536
	v_cmp_lt_i32_e64 s[48:49], s30, v12
	s_nop 1
	v_subbrev_co_u32_e64 v6, s[48:49], 0, v12, s[48:49]
	v_cmp_lt_i32_e64 s[48:49], s91, v6
	s_and_saveexec_b64 s[24:25], s[48:49]
	s_xor_b64 s[24:25], exec, s[24:25]
	v_add_u32_e32 v7, 0xffffff00, v6
	v_lshlrev_b32_e32 v6, 6, v6
	v_lshrrev_b32_e32 v8, 6, v7
	v_and_or_b32 v6, v6, s96, v8
	v_cndmask_b32_e64 v6, v6, v7, s[40:41]
	v_add_u32_e32 v7, s34, v6
	s_andn2_saveexec_b64 s[24:25], s[24:25]
	v_add_u32_e32 v7, s35, v6
	s_or_b64 exec, exec, s[24:25]
	v_mov_b64_e32 v[8:9], s[16:17]
	v_mad_i64_i32 v[6:7], s[24:25], v7, s69, v[8:9]
	v_lshl_add_u64 v[6:7], v[10:11], 1, v[6:7]
	global_load_dwordx4 v[6:9], v[6:7], off offset:1536
	v_add_u32_e32 v13, 1, v12
	v_cmp_gt_i32_e64 s[48:49], s31, v13
	s_nop 1
	v_cndmask_b32_e64 v13, v12, v13, s[48:49]
	v_cmp_lt_i32_e64 s[48:49], s91, v13
	s_and_saveexec_b64 s[24:25], s[48:49]
	s_xor_b64 s[24:25], exec, s[24:25]
	v_add_u32_e32 v12, 0xffffff00, v13
	v_lshlrev_b32_e32 v13, 6, v13
	v_lshrrev_b32_e32 v38, 6, v12
	v_and_or_b32 v13, v13, s96, v38
	v_cndmask_b32_e64 v12, v13, v12, s[40:41]
	v_add_u32_e32 v12, s34, v12
	s_andn2_saveexec_b64 s[24:25], s[24:25]
	v_add_u32_e32 v12, s35, v13
	s_or_b64 exec, exec, s[24:25]
	v_mov_b64_e32 v[38:39], s[16:17]
	v_mad_i64_i32 v[12:13], s[24:25], v12, s69, v[38:39]
	v_lshl_add_u64 v[10:11], v[10:11], 1, v[12:13]
	global_load_dwordx4 v[10:13], v[10:11], off offset:1536
	v_cmp_gt_i32_e64 s[48:49], s39, v0
	s_and_saveexec_b64 s[24:25], s[48:49]
	s_cbranch_execz .LBB0_978
	s_and_saveexec_b64 s[26:27], vcc
	s_xor_b64 s[26:27], exec, s[26:27]
	s_cbranch_execz .LBB0_956
	s_movk_i32 s28, 0x9ff
	v_cmp_lt_u32_e32 vcc, s28, v0
	v_lshlrev_b32_e32 v39, 3, v0
	s_and_saveexec_b64 s[28:29], vcc
	s_xor_b64 s[28:29], exec, s[28:29]
	v_add_u32_e32 v0, 0xfffff600, v0
	v_lshrrev_b32_e32 v52, 4, v0
	v_and_b32_e32 v0, 0x78, v39
	v_or_b32_e32 v38, 0x500, v0
	s_andn2_saveexec_b64 s[28:29], s[28:29]
	v_add_u32_e32 v0, 0xfffff700, v0
	v_lshrrev_b32_e32 v0, 1, v0
	v_and_b32_e32 v38, 56, v39
	v_and_or_b32 v0, v0, s37, v38
	v_add_u32_e32 v38, 0x480, v0
	v_mov_b32_e32 v52, v46
	s_or_b64 exec, exec, s[28:29]
